# prep gating: DPP quad-broadcast fmac chain with the next block row's 16 LDS fragments prefetched (double-buffered), plus the norm-loop load hoist
# baseline (speedup 1.0000x reference)
; __device__ __forceinline__ float bflo(unsigned w) { return __uint_as_float(w << 16); }
; __device__ __forceinline__ float bfhi(unsigned w) { return __uint_as_float(w & 0xffff0000u); }
; __device__ __forceinline__ void prep_phase(const Args& a, LAS unsigned char* lds, int tid, int lane, int wave) {
;     ...
;     for (int wv = BID * NWAVES + wave; wv < Bn * 8 * (S / 64); wv += nwv) {
;         const int bh = __builtin_amdgcn_readfirstlane(wv / (S / 64)), t0 = __builtin_amdgcn_readfirstlane((wv % (S / 64)) * 64);
;         const int b = bh >> 3, h = bh & 7, t = t0 + lane, blk = t0 >> 8;
;         unsigned mask = 1u << blk;
;         if (blk > 0) {
;             float q[64];
;             const v4u* qp = (const v4u*)(Q + ((size_t)(b * S + t)) * D + h * 64);
; #pragma unroll
;             for (int c = 0; c < 8; ++c) { const v4u w = qp[c]; q[8 * c] = bflo(w.x); q[8 * c + 1] = bfhi(w.x); q[8 * c + 2] = bflo(w.y); q[8 * c + 3] = bfhi(w.y); q[8 * c + 4] = bflo(w.z); q[8 * c + 5] = bfhi(w.z); q[8 * c + 6] = bflo(w.w); q[8 * c + 7] = bfhi(w.w); }
;             float g0 = -3e38f, g1 = -3e38f, g2 = -3e38f; int i0 = -1, i1 = -1, i2 = -1;
;             for (int n = 0; n < blk; ++n) {
;                 const float* kb = KBAR + ((size_t)(bh * 32 + n)) * 64; float gsum = 0.f;
; #pragma unroll
;                 for (int d = 0; d < 64; ++d) gsum += q[d] * kb[d];
.LBB0_559:
	s_ashr_i32 s6, s3, 31
	s_lshr_b32 s6, s6, 25
	s_add_i32 s6, s3, s6
	s_ashr_i32 s12, s6, 7
	s_and_b32 s6, s6, 0xffffff80
	s_sub_i32 s10, s3, s6
	s_sub_i32 s98, 0x7f, s10
	s_cmpk_lt_i32 s3, 0x800
	s_cselect_b32 s10, s10, s98
	s_ashr_i32 s11, s10, 2
	s_lshl_b32 s13, 1, s11
	s_cmp_gt_i32 s11, 0
	v_lshl_or_b32 v0, s10, 6, v12
	s_cselect_b64 s[22:23], -1, 0
	s_cmp_lt_i32 s11, 1
	v_mov_b32_e32 v2, s13
	s_cbranch_scc1 .LBB0_570
	s_lshl_b32 s6, s12, 10
	s_and_b32 s6, s6, 0xffffe000
	v_add_u32_e32 v2, s6, v0
	s_waitcnt lgkmcnt(1)
	v_ashrrev_i32_e32 v3, 31, v2
	v_lshlrev_b64 v[2:3], 11, v[2:3]
	s_lshl_b32 s6, s12, 7
	v_lshl_add_u64 v[2:3], s[4:5], 0, v[2:3]
	s_and_b32 s6, s6, 0x380
	v_lshl_add_u64 v[10:11], v[2:3], 0, s[6:7]
	global_load_dwordx4 v[2:5], v[10:11], off
	global_load_dwordx4 v[6:9], v[10:11], off offset:16
	global_load_dwordx4 v[36:39], v[10:11], off offset:32
	global_load_dwordx4 v[46:49], v[10:11], off offset:48
	global_load_dwordx4 v[54:57], v[10:11], off offset:64
	global_load_dwordx4 v[62:65], v[10:11], off offset:80
	global_load_dwordx4 v[68:71], v[10:11], off offset:96
	global_load_dwordx4 v[72:75], v[10:11], off offset:112
	s_lshl_b32 s8, s12, 5
	s_ashr_i32 s9, s8, 31
	s_lshl_b64 s[8:9], s[8:9], 8
	s_add_u32 s24, s19, s8
	v_mov_b32_e32 v50, 0xff61b1e6
	v_mov_b32_e32 v44, -1
	s_addc_u32 s25, s20, s9
	v_and_b32_e32 v140, 63, v254
	v_lshlrev_b32_e32 v141, 4, v140
	v_add_u32_e32 v142, 0x1000, v141
	global_load_dwordx4 v[144:147], v141, s[24:25]
	global_load_dwordx4 v[148:151], v141, s[24:25] offset:1024
	global_load_dwordx4 v[152:155], v141, s[24:25] offset:2048
	global_load_dwordx4 v[156:159], v141, s[24:25] offset:3072
	global_load_dwordx4 v[160:163], v142, s[24:25]
	global_load_dwordx4 v[164:167], v142, s[24:25] offset:1024
	global_load_dwordx4 v[168:171], v142, s[24:25] offset:2048
	global_load_dwordx4 v[172:175], v142, s[24:25] offset:3072
	v_lshrrev_b32_e32 v143, 6, v254
	v_lshlrev_b32_e32 v143, 13, v143
	v_add_u32_e32 v140, v143, v141
	s_mov_b32 s6, 0
	s_waitcnt vmcnt(7) lgkmcnt(0)
	v_lshlrev_b32_e32 v1, 16, v2
	v_and_b32_e32 v17, 0xffff0000, v2
	v_lshlrev_b32_e32 v18, 16, v3
	v_and_b32_e32 v19, 0xffff0000, v3
	v_lshlrev_b32_e32 v20, 16, v4
	v_and_b32_e32 v21, 0xffff0000, v4
	v_lshlrev_b32_e32 v22, 16, v5
	v_and_b32_e32 v23, 0xffff0000, v5
	s_waitcnt vmcnt(6)
	v_lshlrev_b32_e32 v24, 16, v6
	v_and_b32_e32 v25, 0xffff0000, v6
	v_lshlrev_b32_e32 v26, 16, v7
	v_and_b32_e32 v27, 0xffff0000, v7
	v_lshlrev_b32_e32 v28, 16, v8
	v_and_b32_e32 v29, 0xffff0000, v8
	v_lshlrev_b32_e32 v30, 16, v9
	v_and_b32_e32 v31, 0xffff0000, v9
	s_waitcnt vmcnt(5)
	v_lshlrev_b32_e32 v32, 16, v36
	v_and_b32_e32 v33, 0xffff0000, v36
	v_lshlrev_b32_e32 v34, 16, v37
	v_and_b32_e32 v35, 0xffff0000, v37
	v_lshlrev_b32_e32 v36, 16, v38
	v_and_b32_e32 v37, 0xffff0000, v38
	v_lshlrev_b32_e32 v38, 16, v39
	v_and_b32_e32 v39, 0xffff0000, v39
	s_waitcnt vmcnt(4)
	v_lshlrev_b32_e32 v40, 16, v46
	v_and_b32_e32 v41, 0xffff0000, v46
	v_lshlrev_b32_e32 v42, 16, v47
	v_and_b32_e32 v43, 0xffff0000, v47
	v_lshlrev_b32_e32 v45, 16, v48
	v_and_b32_e32 v46, 0xffff0000, v48
	v_lshlrev_b32_e32 v47, 16, v49
	v_and_b32_e32 v48, 0xffff0000, v49
	s_waitcnt vmcnt(3)
	v_lshlrev_b32_e32 v49, 16, v54
	v_and_b32_e32 v51, 0xffff0000, v54
	v_lshlrev_b32_e32 v52, 16, v55
	v_and_b32_e32 v53, 0xffff0000, v55
	v_lshlrev_b32_e32 v54, 16, v56
	v_and_b32_e32 v55, 0xffff0000, v56
	v_lshlrev_b32_e32 v56, 16, v57
	v_and_b32_e32 v57, 0xffff0000, v57
	s_waitcnt vmcnt(2)
	v_lshlrev_b32_e32 v58, 16, v62
	v_and_b32_e32 v59, 0xffff0000, v62
	v_lshlrev_b32_e32 v60, 16, v63
	v_and_b32_e32 v61, 0xffff0000, v63
	v_lshlrev_b32_e32 v62, 16, v64
	v_and_b32_e32 v63, 0xffff0000, v64
	v_lshlrev_b32_e32 v64, 16, v65
	v_and_b32_e32 v65, 0xffff0000, v65
	s_waitcnt vmcnt(1)
	v_lshlrev_b32_e32 v66, 16, v68
	v_and_b32_e32 v67, 0xffff0000, v68
	v_lshlrev_b32_e32 v68, 16, v69
	v_and_b32_e32 v69, 0xffff0000, v69
	v_lshlrev_b32_e32 v2, 16, v70
	v_and_b32_e32 v3, 0xffff0000, v70
	v_lshlrev_b32_e32 v4, 16, v71
	v_and_b32_e32 v5, 0xffff0000, v71
	s_waitcnt vmcnt(0)
	ds_write_b128 v140, v[144:147]
	ds_write_b128 v140, v[148:151] offset:1024
	ds_write_b128 v140, v[152:155] offset:2048
	ds_write_b128 v140, v[156:159] offset:3072
	ds_write_b128 v140, v[160:163] offset:4096
	ds_write_b128 v140, v[164:167] offset:5120
	ds_write_b128 v140, v[168:171] offset:6144
	ds_write_b128 v140, v[172:175] offset:7168
	v_and_b32_e32 v141, 3, v254
	v_lshlrev_b32_e32 v141, 2, v141
	v_add_u32_e32 v143, v143, v141
	s_waitcnt lgkmcnt(0)
	ds_read_b32 v224, v143
	ds_read_b32 v225, v143 offset:16
	ds_read_b32 v226, v143 offset:32
	ds_read_b32 v227, v143 offset:48
	ds_read_b32 v228, v143 offset:64
	ds_read_b32 v229, v143 offset:80
	ds_read_b32 v230, v143 offset:96
	ds_read_b32 v231, v143 offset:112
	ds_read_b32 v232, v143 offset:128
	ds_read_b32 v233, v143 offset:144
	ds_read_b32 v234, v143 offset:160
	ds_read_b32 v235, v143 offset:176
	ds_read_b32 v236, v143 offset:192
	ds_read_b32 v237, v143 offset:208
	ds_read_b32 v238, v143 offset:224
	ds_read_b32 v239, v143 offset:240
	v_lshlrev_b32_e32 v6, 16, v72
	v_and_b32_e32 v7, 0xffff0000, v72
	v_lshlrev_b32_e32 v8, 16, v73
	v_and_b32_e32 v9, 0xffff0000, v73
	v_lshlrev_b32_e32 v10, 16, v74
	v_and_b32_e32 v11, 0xffff0000, v74
	v_lshlrev_b32_e32 v14, 16, v75
	v_and_b32_e32 v15, 0xffff0000, v75
	v_mov_b32_e32 v70, -1
	v_mov_b32_e32 v71, -1
	v_mov_b32_e32 v72, 0xff61b1e6
	v_mov_b32_e32 v73, 0xff61b1e6
; __device__ __forceinline__ void prep_phase(const Args& a, LAS unsigned char* lds, int tid, int lane, int wave) {
;     ...
;             for (int n = 0; n < blk; ++n) {
;                 const float* kb = KBAR + ((size_t)(bh * 32 + n)) * 64; float gsum = 0.f;
; #pragma unroll
;                 for (int d = 0; d < 64; ++d) gsum += q[d] * kb[d];
;                 if (gsum > g0) { g2 = g1; i2 = i1; g1 = g0; i1 = i0; g0 = gsum; i0 = n; }
;                 else if (gsum > g1) { g2 = g1; i2 = i1; g1 = gsum; i1 = n; }
;                 else if (gsum > g2) { g2 = gsum; i2 = n; }
;             }
.LBB0_561:
	s_waitcnt lgkmcnt(0)
	v_mov_b32_e32 v208, v224
	v_mov_b32_e32 v209, v225
	v_mov_b32_e32 v210, v226
	v_mov_b32_e32 v211, v227
	v_mov_b32_e32 v212, v228
	v_mov_b32_e32 v213, v229
	v_mov_b32_e32 v214, v230
	v_mov_b32_e32 v215, v231
	v_mov_b32_e32 v216, v232
	v_mov_b32_e32 v217, v233
	v_mov_b32_e32 v218, v234
	v_mov_b32_e32 v219, v235
	v_mov_b32_e32 v220, v236
	v_mov_b32_e32 v221, v237
	v_mov_b32_e32 v222, v238
	v_mov_b32_e32 v223, v239
	v_add_u32_e32 v143, 0x100, v143
	ds_read_b32 v224, v143
	ds_read_b32 v225, v143 offset:16
	ds_read_b32 v226, v143 offset:32
	ds_read_b32 v227, v143 offset:48
	ds_read_b32 v228, v143 offset:64
	ds_read_b32 v229, v143 offset:80
	ds_read_b32 v230, v143 offset:96
	ds_read_b32 v231, v143 offset:112
	ds_read_b32 v232, v143 offset:128
	ds_read_b32 v233, v143 offset:144
	ds_read_b32 v234, v143 offset:160
	ds_read_b32 v235, v143 offset:176
	ds_read_b32 v236, v143 offset:192
	ds_read_b32 v237, v143 offset:208
	ds_read_b32 v238, v143 offset:224
	ds_read_b32 v239, v143 offset:240
	v_mov_b32_e32 v74, 0
	s_nop 1
	v_fmac_f32_dpp v74, v208, v1 quad_perm:[0,0,0,0] row_mask:0xf bank_mask:0xf
	v_fmac_f32_dpp v74, v208, v17 quad_perm:[1,1,1,1] row_mask:0xf bank_mask:0xf
	v_fmac_f32_dpp v74, v208, v18 quad_perm:[2,2,2,2] row_mask:0xf bank_mask:0xf
	v_fmac_f32_dpp v74, v208, v19 quad_perm:[3,3,3,3] row_mask:0xf bank_mask:0xf
	v_fmac_f32_dpp v74, v209, v20 quad_perm:[0,0,0,0] row_mask:0xf bank_mask:0xf
	v_fmac_f32_dpp v74, v209, v21 quad_perm:[1,1,1,1] row_mask:0xf bank_mask:0xf
	v_fmac_f32_dpp v74, v209, v22 quad_perm:[2,2,2,2] row_mask:0xf bank_mask:0xf
	v_fmac_f32_dpp v74, v209, v23 quad_perm:[3,3,3,3] row_mask:0xf bank_mask:0xf
	v_fmac_f32_dpp v74, v210, v24 quad_perm:[0,0,0,0] row_mask:0xf bank_mask:0xf
	v_fmac_f32_dpp v74, v210, v25 quad_perm:[1,1,1,1] row_mask:0xf bank_mask:0xf
	v_fmac_f32_dpp v74, v210, v26 quad_perm:[2,2,2,2] row_mask:0xf bank_mask:0xf
	v_fmac_f32_dpp v74, v210, v27 quad_perm:[3,3,3,3] row_mask:0xf bank_mask:0xf
	v_fmac_f32_dpp v74, v211, v28 quad_perm:[0,0,0,0] row_mask:0xf bank_mask:0xf
	v_fmac_f32_dpp v74, v211, v29 quad_perm:[1,1,1,1] row_mask:0xf bank_mask:0xf
	v_fmac_f32_dpp v74, v211, v30 quad_perm:[2,2,2,2] row_mask:0xf bank_mask:0xf
	v_fmac_f32_dpp v74, v211, v31 quad_perm:[3,3,3,3] row_mask:0xf bank_mask:0xf
	v_fmac_f32_dpp v74, v212, v32 quad_perm:[0,0,0,0] row_mask:0xf bank_mask:0xf
	v_fmac_f32_dpp v74, v212, v33 quad_perm:[1,1,1,1] row_mask:0xf bank_mask:0xf
	v_fmac_f32_dpp v74, v212, v34 quad_perm:[2,2,2,2] row_mask:0xf bank_mask:0xf
	v_fmac_f32_dpp v74, v212, v35 quad_perm:[3,3,3,3] row_mask:0xf bank_mask:0xf
	v_fmac_f32_dpp v74, v213, v36 quad_perm:[0,0,0,0] row_mask:0xf bank_mask:0xf
	v_fmac_f32_dpp v74, v213, v37 quad_perm:[1,1,1,1] row_mask:0xf bank_mask:0xf
	v_fmac_f32_dpp v74, v213, v38 quad_perm:[2,2,2,2] row_mask:0xf bank_mask:0xf
	v_fmac_f32_dpp v74, v213, v39 quad_perm:[3,3,3,3] row_mask:0xf bank_mask:0xf
	v_fmac_f32_dpp v74, v214, v40 quad_perm:[0,0,0,0] row_mask:0xf bank_mask:0xf
	v_fmac_f32_dpp v74, v214, v41 quad_perm:[1,1,1,1] row_mask:0xf bank_mask:0xf
	v_fmac_f32_dpp v74, v214, v42 quad_perm:[2,2,2,2] row_mask:0xf bank_mask:0xf
	v_fmac_f32_dpp v74, v214, v43 quad_perm:[3,3,3,3] row_mask:0xf bank_mask:0xf
	v_fmac_f32_dpp v74, v215, v45 quad_perm:[0,0,0,0] row_mask:0xf bank_mask:0xf
	v_fmac_f32_dpp v74, v215, v46 quad_perm:[1,1,1,1] row_mask:0xf bank_mask:0xf
	v_fmac_f32_dpp v74, v215, v47 quad_perm:[2,2,2,2] row_mask:0xf bank_mask:0xf
	v_fmac_f32_dpp v74, v215, v48 quad_perm:[3,3,3,3] row_mask:0xf bank_mask:0xf
	v_fmac_f32_dpp v74, v216, v49 quad_perm:[0,0,0,0] row_mask:0xf bank_mask:0xf
	v_fmac_f32_dpp v74, v216, v51 quad_perm:[1,1,1,1] row_mask:0xf bank_mask:0xf
	v_fmac_f32_dpp v74, v216, v52 quad_perm:[2,2,2,2] row_mask:0xf bank_mask:0xf
	v_fmac_f32_dpp v74, v216, v53 quad_perm:[3,3,3,3] row_mask:0xf bank_mask:0xf
	v_fmac_f32_dpp v74, v217, v54 quad_perm:[0,0,0,0] row_mask:0xf bank_mask:0xf
	v_fmac_f32_dpp v74, v217, v55 quad_perm:[1,1,1,1] row_mask:0xf bank_mask:0xf
	v_fmac_f32_dpp v74, v217, v56 quad_perm:[2,2,2,2] row_mask:0xf bank_mask:0xf
	v_fmac_f32_dpp v74, v217, v57 quad_perm:[3,3,3,3] row_mask:0xf bank_mask:0xf
	v_fmac_f32_dpp v74, v218, v58 quad_perm:[0,0,0,0] row_mask:0xf bank_mask:0xf
	v_fmac_f32_dpp v74, v218, v59 quad_perm:[1,1,1,1] row_mask:0xf bank_mask:0xf
	v_fmac_f32_dpp v74, v218, v60 quad_perm:[2,2,2,2] row_mask:0xf bank_mask:0xf
	v_fmac_f32_dpp v74, v218, v61 quad_perm:[3,3,3,3] row_mask:0xf bank_mask:0xf
	v_fmac_f32_dpp v74, v219, v62 quad_perm:[0,0,0,0] row_mask:0xf bank_mask:0xf
	v_fmac_f32_dpp v74, v219, v63 quad_perm:[1,1,1,1] row_mask:0xf bank_mask:0xf
	v_fmac_f32_dpp v74, v219, v64 quad_perm:[2,2,2,2] row_mask:0xf bank_mask:0xf
	v_fmac_f32_dpp v74, v219, v65 quad_perm:[3,3,3,3] row_mask:0xf bank_mask:0xf
	v_fmac_f32_dpp v74, v220, v66 quad_perm:[0,0,0,0] row_mask:0xf bank_mask:0xf
	v_fmac_f32_dpp v74, v220, v67 quad_perm:[1,1,1,1] row_mask:0xf bank_mask:0xf
	v_fmac_f32_dpp v74, v220, v68 quad_perm:[2,2,2,2] row_mask:0xf bank_mask:0xf
	v_mul_f32_dpp v78, v221, v2 quad_perm:[0,0,0,0] row_mask:0xf bank_mask:0xf
	v_mul_f32_dpp v79, v221, v3 quad_perm:[1,1,1,1] row_mask:0xf bank_mask:0xf
	v_fmac_f32_dpp v74, v220, v69 quad_perm:[3,3,3,3] row_mask:0xf bank_mask:0xf
	v_add_f32_e32 v74, v74, v78
	v_mul_f32_dpp v80, v221, v4 quad_perm:[2,2,2,2] row_mask:0xf bank_mask:0xf
	v_mul_f32_dpp v81, v221, v5 quad_perm:[3,3,3,3] row_mask:0xf bank_mask:0xf
	v_add_f32_e32 v74, v74, v79
	v_add_f32_e32 v74, v74, v80
	v_mul_f32_dpp v82, v222, v6 quad_perm:[0,0,0,0] row_mask:0xf bank_mask:0xf
	v_mul_f32_dpp v83, v222, v7 quad_perm:[1,1,1,1] row_mask:0xf bank_mask:0xf
	v_add_f32_e32 v74, v74, v81
	v_add_f32_e32 v74, v74, v82
	v_mul_f32_dpp v84, v222, v8 quad_perm:[2,2,2,2] row_mask:0xf bank_mask:0xf
	v_mul_f32_dpp v85, v222, v9 quad_perm:[3,3,3,3] row_mask:0xf bank_mask:0xf
	v_add_f32_e32 v74, v74, v83
	v_add_f32_e32 v74, v74, v84
	v_mul_f32_dpp v86, v223, v10 quad_perm:[0,0,0,0] row_mask:0xf bank_mask:0xf
	v_mul_f32_dpp v87, v223, v11 quad_perm:[1,1,1,1] row_mask:0xf bank_mask:0xf
	v_add_f32_e32 v74, v74, v85
	v_add_f32_e32 v74, v74, v86
	v_mul_f32_dpp v88, v223, v14 quad_perm:[2,2,2,2] row_mask:0xf bank_mask:0xf
	v_mul_f32_dpp v89, v223, v15 quad_perm:[3,3,3,3] row_mask:0xf bank_mask:0xf
	v_add_f32_e32 v74, v74, v87
	v_add_f32_e32 v74, v74, v88
	v_add_f32_e32 v74, v74, v89
	v_cmp_ngt_f32_e32 vcc, v74, v73
	v_mov_b32_e32 v75, s6
	s_and_saveexec_b64 s[26:27], vcc
	s_cbranch_execz .LBB0_567
	v_cmp_ngt_f32_e32 vcc, v74, v72
	v_mov_b32_e32 v76, s6
	s_and_saveexec_b64 s[28:29], vcc
	s_cbranch_execz .LBB0_566
	v_cmp_gt_f32_e32 vcc, v74, v50
	s_and_saveexec_b64 s[8:9], vcc
	v_mov_b32_e32 v44, s6
	v_mov_b32_e32 v50, v74
	s_or_b64 exec, exec, s[8:9]
	v_mov_b32_e32 v76, v70
	v_mov_b32_e32 v74, v72
	v_mov_b32_e32 v72, v50
	v_mov_b32_e32 v70, v44
